# P0 two-class variant: even workgroups x rows -> rope -> weight items, odd workgroups rope -> weight items -> x rows (x-row HBM traffic spread over the whole phase)
# speedup vs baseline: 1.0078x; 1.0044x over previous
.LBB0_10:
	s_or_b64 exec, exec, s[2:3]
	s_load_dwordx16 s[72:87], s[0:1], 0x40
	v_readlane_b32 s0, v254, 5
	s_lshr_b32 s89, s0, 6
	v_readlane_b32 s0, v254, 9
	v_readlane_b32 s1, v254, 10
	v_readlane_b32 s2, v254, 11
	v_readlane_b32 s3, v254, 12
	s_cmp_lt_i32 s0, 1
	s_cselect_b64 s[2:3], -1, 0
	s_cmp_gt_i32 s1, 0
	s_cselect_b64 s[0:1], -1, 0
	v_writelane_b32 v254, s2, 31
	s_and_b64 s[6:7], s[2:3], s[0:1]
	s_andn2_b64 vcc, exec, s[6:7]
	v_and_b32_e32 v227, 63, v226
	v_writelane_b32 v254, s3, 32
	s_cbranch_vccnz .LBB0_183
	s_and_b32 s99, s88, 1
	s_sub_u32 s99, 2, s99
	s_cmp_eq_u32 s99, 0
	s_cbranch_scc1 .Lp0_front
	s_cmp_eq_u32 s99, 1
	s_cbranch_scc1 .LBB0_163
	s_mov_b32 s99, 3
	s_lshl_b32 s0, s88, 3
	s_add_i32 s8, s89, s0
	s_lshl_b32 s10, s90, 3
	s_branch .LBB0_158
